# v35 + phase-0 tiles: all 4 row-group loads issued together (3 extra into spare regs), later reloads replaced by register moves
# speedup vs baseline: 1.0113x; 1.0050x over previous
.LBB0_441:
	s_cmpk_gt_i32 s11, 0x2ff
	s_mov_b64 s[12:13], -1
	s_cbranch_scc0 .LBB0_479
	s_cmpk_gt_u32 s11, 0x3ff
	s_cbranch_scc0 .LBB0_476
	s_cmpk_gt_u32 s11, 0x4ff
	s_cbranch_scc0 .LBB0_465
	s_add_i32 s0, s11, 0xfffffb00
	s_cmp_ge_i32 s0, s1
	s_cbranch_scc0 .LBB0_462
	s_add_i32 s16, s47, s11
	s_cmpk_gt_i32 s16, 0xff
	s_cbranch_scc0 .LBB0_459
	s_cmpk_gt_u32 s16, 0x67f
	s_cbranch_scc0 .LBB0_448
	s_load_dwordx2 s[12:13], s[58:59], 0xb0
	v_mov_b32_e32 v8, v243
	s_waitcnt lgkmcnt(0)
	v_ashrrev_i32_e32 v9, 4, v8
	s_add_u32 s14, s12, s19
	s_addc_u32 s13, s13, s18
	s_add_i32 s12, s44, s45
	s_and_b32 s17, s12, 0x7fffffc0
	s_and_b32 s12, s42, 0x3c0
	s_lshl_b32 s15, s12, 2
	s_add_u32 s14, s14, s15
	v_lshlrev_b32_e32 v0, 4, v8
	v_add_u32_e32 v2, s17, v9
	s_addc_u32 s15, s13, 0
	v_and_b32_e32 v0, 0xf0, v0
	v_ashrrev_i32_e32 v3, 31, v2
	v_lshl_add_u64 v[6:7], s[14:15], 0, v[0:1]
	v_lshlrev_b64 v[2:3], 12, v[2:3]
	v_lshl_add_u64 v[2:3], v[6:7], 0, v[2:3]
	v_mov_b32_e32 v70, 0x10000
	v_mov_b32_e32 v71, 0
	v_lshl_add_u64 v[72:73], v[2:3], 0, v[70:71]
	v_lshl_add_u64 v[74:75], v[72:73], 0, v[70:71]
	v_lshl_add_u64 v[76:77], v[74:75], 0, v[70:71]
	s_barrier
	global_load_dwordx4 v[2:5], v[2:3], off
	global_load_dwordx4 v[80:83], v[72:73], off
	global_load_dwordx4 v[84:87], v[74:75], off
	global_load_dwordx4 v[88:91], v[76:77], off
	v_mul_lo_u32 v9, v9, s77
	v_add3_u32 v9, s78, v9, v0
	v_add_u32_e32 v10, 0x100, v8
	s_lshl_b32 s13, s17, 1
	s_add_u32 s14, s20, s13
	s_addc_u32 s15, s21, 0
	s_movk_i32 s13, 0x1600
	s_waitcnt vmcnt(0)
	ds_write2_b32 v9, v2, v3 offset1:1
	ds_write2_b32 v9, v4, v5 offset0:2 offset1:3
	v_ashrrev_i32_e32 v9, 4, v10
	v_add_u32_e32 v2, s17, v9
	v_ashrrev_i32_e32 v3, 31, v2
	v_lshlrev_b64 v[2:3], 12, v[2:3]
	v_lshl_add_u64 v[2:3], v[6:7], 0, v[2:3]
	v_mov_b32_e32 v2, v80
	v_mov_b32_e32 v3, v81
	v_mov_b32_e32 v4, v82
	v_mov_b32_e32 v5, v83
	v_mul_lo_u32 v9, v9, s77
	v_add3_u32 v9, s78, v9, v0
	s_waitcnt vmcnt(0)
	ds_write2_b32 v9, v2, v3 offset1:1
	ds_write2_b32 v9, v4, v5 offset0:2 offset1:3
	v_add_u32_e32 v2, 0x200, v8
	v_ashrrev_i32_e32 v9, 4, v2
	v_add_u32_e32 v2, s17, v9
	v_ashrrev_i32_e32 v3, 31, v2
	v_lshlrev_b64 v[2:3], 12, v[2:3]
	v_lshl_add_u64 v[2:3], v[6:7], 0, v[2:3]
	v_mov_b32_e32 v2, v84
	v_mov_b32_e32 v3, v85
	v_mov_b32_e32 v4, v86
	v_mov_b32_e32 v5, v87
	v_mul_lo_u32 v9, v9, s77
	v_add3_u32 v9, s78, v9, v0
	s_waitcnt vmcnt(0)
	ds_write2_b32 v9, v2, v3 offset1:1
	ds_write2_b32 v9, v4, v5 offset0:2 offset1:3
	v_add_u32_e32 v2, 0x300, v8
	v_ashrrev_i32_e32 v9, 4, v2
	v_add_u32_e32 v2, s17, v9
	v_ashrrev_i32_e32 v3, 31, v2
	v_lshlrev_b64 v[2:3], 12, v[2:3]
	v_lshl_add_u64 v[2:3], v[6:7], 0, v[2:3]
	v_mov_b32_e32 v2, v88
	v_mov_b32_e32 v3, v89
	v_mov_b32_e32 v4, v90
	v_mov_b32_e32 v5, v91
	v_mul_lo_u32 v6, v9, s77
	v_add3_u32 v0, s78, v6, v0
	s_waitcnt vmcnt(0)
	ds_write2_b32 v0, v2, v3 offset1:1
	ds_write2_b32 v0, v4, v5 offset0:2 offset1:3
	v_lshlrev_b32_e32 v0, 3, v8
	v_and_b32_e32 v0, 56, v0
	v_mul_u32_u24_e32 v4, 0x41, v0
	v_lshlrev_b32_e32 v0, 1, v0
	v_lshl_add_u64 v[2:3], s[14:15], 0, v[0:1]
	v_ashrrev_i32_e32 v0, 3, v8
	v_lshlrev_b32_e32 v5, 2, v0
	v_lshlrev_b32_e32 v11, 2, v4
	v_add3_u32 v8, s78, v5, v11
	s_waitcnt lgkmcnt(0)
	s_barrier
	ds_read2_b32 v[4:5], v8 offset1:65
	ds_read2_b32 v[6:7], v8 offset0:130 offset1:195
	v_add_u32_e32 v8, 0x400, v8
	v_add_u32_e32 v0, s12, v0
	s_waitcnt lgkmcnt(1)
	v_cvt_pk_bf16_f32 v4, v4, v5
	s_waitcnt lgkmcnt(0)
	v_cvt_pk_bf16_f32 v5, v6, v7
	ds_read2_b32 v[6:7], v8 offset0:4 offset1:69
	ds_read2_b32 v[8:9], v8 offset0:134 offset1:199
	s_waitcnt lgkmcnt(1)
	v_cvt_pk_bf16_f32 v6, v6, v7
	s_waitcnt lgkmcnt(0)
	v_cvt_pk_bf16_f32 v7, v8, v9
	v_mad_i64_i32 v[8:9], s[14:15], v0, s13, v[2:3]
	v_ashrrev_i32_e32 v0, 3, v10
	global_store_dwordx4 v[8:9], v[4:7], off
	s_nop 1
	v_lshlrev_b32_e32 v4, 2, v0
	v_add3_u32 v8, s78, v4, v11
	ds_read2_b32 v[4:5], v8 offset1:65
	ds_read2_b32 v[6:7], v8 offset0:130 offset1:195
	v_add_u32_e32 v8, 0x400, v8
	v_add_u32_e32 v0, s12, v0
	v_mad_i64_i32 v[2:3], s[12:13], v0, s13, v[2:3]
	s_waitcnt lgkmcnt(1)
	v_cvt_pk_bf16_f32 v4, v4, v5
	s_waitcnt lgkmcnt(0)
	v_cvt_pk_bf16_f32 v5, v6, v7
	ds_read2_b32 v[6:7], v8 offset0:4 offset1:69
	ds_read2_b32 v[8:9], v8 offset0:134 offset1:199
	s_mov_b64 s[12:13], 0
	s_waitcnt lgkmcnt(1)
	v_cvt_pk_bf16_f32 v6, v6, v7
	s_waitcnt lgkmcnt(0)
	v_cvt_pk_bf16_f32 v7, v8, v9
	global_store_dwordx4 v[2:3], v[4:7], off
.LBB0_448:
	s_andn2_b64 vcc, exec, s[12:13]
	s_cbranch_vccnz .LBB0_458
	s_load_dwordx2 s[12:13], s[58:59], 0xa0
	s_load_dwordx2 s[38:39], s[58:59], 0x28
	v_mov_b32_e32 v10, v243
	s_waitcnt lgkmcnt(0)
	s_add_u32 s14, s12, s23
	s_addc_u32 s15, s13, s22
	s_lshl_b64 s[12:13], s[4:5], 2
	s_add_u32 s12, s38, s12
	s_addc_u32 s13, s39, s13
	s_add_i32 s52, s16, 0xff00
	s_and_b32 s17, s52, 0xffff
	s_mul_i32 s17, s17, 0xba2f
	s_lshr_b32 s53, s17, 22
	s_mulk_i32 s53, 0x58
	s_sub_i32 s52, s52, s53
	s_lshr_b32 s17, s17, 16
	s_lshl_b32 s53, s52, 8
	s_and_b32 s17, s17, 0xffc0
	s_and_b32 s53, s53, 0x3ff00
	v_lshlrev_b32_e32 v0, 2, v10
	s_add_u32 s14, s14, s53
	v_and_b32_e32 v0, 60, v0
	s_addc_u32 s15, s15, 0
	v_lshlrev_b32_e32 v0, 2, v0
	v_ashrrev_i32_e32 v11, 4, v10
	v_lshl_add_u64 v[6:7], s[14:15], 0, v[0:1]
	v_add_u32_e32 v8, s17, v11
	v_mad_i64_i32 v[2:3], s[14:15], v8, s74, v[6:7]
	v_mov_b32_e32 v70, s74
	v_lshlrev_b32_e32 v70, 4, v70
	v_mov_b32_e32 v71, 0
	v_lshl_add_u64 v[72:73], v[2:3], 0, v[70:71]
	v_lshl_add_u64 v[74:75], v[72:73], 0, v[70:71]
	v_lshl_add_u64 v[76:77], v[74:75], 0, v[70:71]
	s_barrier
	global_load_dwordx4 v[2:5], v[2:3], off
	global_load_dwordx4 v[80:83], v[72:73], off
	global_load_dwordx4 v[84:87], v[74:75], off
	global_load_dwordx4 v[88:91], v[76:77], off
	s_cmp_lg_u64 s[38:39], 0
	s_cselect_b64 s[14:15], -1, 0
	s_cmp_eq_u64 s[38:39], 0
	s_cbranch_scc1 .LBB0_451
	v_ashrrev_i32_e32 v9, 31, v8
	v_lshl_add_u64 v[8:9], v[8:9], 2, s[12:13]
	global_load_dword v8, v[8:9], off
	s_waitcnt vmcnt(0)
	v_pk_mul_f32 v[4:5], v[4:5], v[8:9] op_sel_hi:[1,0]
	v_pk_mul_f32 v[2:3], v[2:3], v[8:9] op_sel_hi:[1,0]
.LBB0_451:
	v_mul_lo_u32 v8, v11, s77
	v_add_u32_e32 v11, 0x100, v10
	v_add3_u32 v8, s78, v8, v0
	v_ashrrev_i32_e32 v12, 4, v11
	s_waitcnt vmcnt(0)
	ds_write2_b32 v8, v2, v3 offset1:1
	ds_write2_b32 v8, v4, v5 offset0:2 offset1:3
	v_add_u32_e32 v8, s17, v12
	v_mad_i64_i32 v[2:3], s[38:39], v8, s74, v[6:7]
	v_mov_b32_e32 v2, v80
	v_mov_b32_e32 v3, v81
	v_mov_b32_e32 v4, v82
	v_mov_b32_e32 v5, v83
	v_cndmask_b32_e64 v9, 0, 1, s[14:15]
	v_cmp_ne_u32_e64 s[38:39], 1, v9
	s_andn2_b64 vcc, exec, s[14:15]
	s_cbranch_vccnz .LBB0_453
	v_ashrrev_i32_e32 v9, 31, v8
	v_lshl_add_u64 v[8:9], v[8:9], 2, s[12:13]
	global_load_dword v8, v[8:9], off
	s_waitcnt vmcnt(0)
	v_pk_mul_f32 v[4:5], v[4:5], v[8:9] op_sel_hi:[1,0]
	v_pk_mul_f32 v[2:3], v[2:3], v[8:9] op_sel_hi:[1,0]
.LBB0_453:
	v_mul_lo_u32 v8, v12, s77
	v_add3_u32 v8, s78, v8, v0
	s_waitcnt vmcnt(0)
	ds_write2_b32 v8, v2, v3 offset1:1
	ds_write2_b32 v8, v4, v5 offset0:2 offset1:3
	v_add_u32_e32 v2, 0x200, v10
	v_ashrrev_i32_e32 v12, 4, v2
	v_add_u32_e32 v8, s17, v12
	v_mad_i64_i32 v[2:3], s[14:15], v8, s74, v[6:7]
	v_mov_b32_e32 v2, v84
	v_mov_b32_e32 v3, v85
	v_mov_b32_e32 v4, v86
	v_mov_b32_e32 v5, v87
	s_and_b64 vcc, exec, s[38:39]
	s_cbranch_vccnz .LBB0_455
	v_ashrrev_i32_e32 v9, 31, v8
	v_lshl_add_u64 v[8:9], v[8:9], 2, s[12:13]
	global_load_dword v8, v[8:9], off
	s_waitcnt vmcnt(0)
	v_pk_mul_f32 v[4:5], v[4:5], v[8:9] op_sel_hi:[1,0]
	v_pk_mul_f32 v[2:3], v[2:3], v[8:9] op_sel_hi:[1,0]
.LBB0_455:
	v_mul_lo_u32 v8, v12, s77
	v_add3_u32 v8, s78, v8, v0
	s_waitcnt vmcnt(0)
	ds_write2_b32 v8, v2, v3 offset1:1
	ds_write2_b32 v8, v4, v5 offset0:2 offset1:3
	v_add_u32_e32 v2, 0x300, v10
	v_ashrrev_i32_e32 v12, 4, v2
	v_add_u32_e32 v8, s17, v12
	v_mad_i64_i32 v[2:3], s[14:15], v8, s74, v[6:7]
	v_mov_b32_e32 v2, v88
	v_mov_b32_e32 v3, v89
	v_mov_b32_e32 v4, v90
	v_mov_b32_e32 v5, v91
	s_and_b64 vcc, exec, s[38:39]
	s_cbranch_vccnz .LBB0_457
	v_ashrrev_i32_e32 v9, 31, v8
	v_lshl_add_u64 v[6:7], v[8:9], 2, s[12:13]
	global_load_dword v6, v[6:7], off
	s_waitcnt vmcnt(0)
	v_pk_mul_f32 v[4:5], v[4:5], v[6:7] op_sel_hi:[1,0]
	v_pk_mul_f32 v[2:3], v[2:3], v[6:7] op_sel_hi:[1,0]

.LBB0_459:
	s_andn2_b64 vcc, exec, s[12:13]
	s_cbranch_vccnz .LBB0_461
	s_load_dwordx2 s[12:13], s[58:59], 0x98
	v_mov_b32_e32 v8, v243
	s_waitcnt lgkmcnt(0)
	v_ashrrev_i32_e32 v9, 4, v8
	s_add_u32 s15, s12, s6
	s_sext_i32_i16 s12, s16
	s_addc_u32 s38, s13, s7
	s_bfe_u32 s12, s12, 0x4001b
	s_add_i32 s12, s16, s12
	s_sext_i32_i16 s13, s12
	s_and_b32 s12, s12, 0xfff0
	s_sub_i32 s12, s16, s12
	s_sext_i32_i16 s12, s12
	s_lshl_b32 s13, s13, 2
	s_lshl_b32 s12, s12, 6
	s_and_b32 s14, s13, 0xffffffc0
	s_ashr_i32 s13, s12, 31
	s_lshl_b64 s[16:17], s[12:13], 2
	s_add_u32 s16, s15, s16
	v_lshlrev_b32_e32 v0, 4, v8
	v_add_u32_e32 v2, s14, v9
	s_addc_u32 s17, s38, s17
	v_and_b32_e32 v0, 0xf0, v0
	v_ashrrev_i32_e32 v3, 31, v2
	v_lshl_add_u64 v[6:7], s[16:17], 0, v[0:1]
	v_lshlrev_b64 v[2:3], 12, v[2:3]
	v_lshl_add_u64 v[2:3], v[6:7], 0, v[2:3]
	v_mov_b32_e32 v70, 0x10000
	v_mov_b32_e32 v71, 0
	v_lshl_add_u64 v[72:73], v[2:3], 0, v[70:71]
	v_lshl_add_u64 v[74:75], v[72:73], 0, v[70:71]
	v_lshl_add_u64 v[76:77], v[74:75], 0, v[70:71]
	s_barrier
	global_load_dwordx4 v[2:5], v[2:3], off
	global_load_dwordx4 v[80:83], v[72:73], off
	global_load_dwordx4 v[84:87], v[74:75], off
	global_load_dwordx4 v[88:91], v[76:77], off
	v_mul_lo_u32 v9, v9, s77
	v_add3_u32 v9, s78, v9, v0
	v_add_u32_e32 v10, 0x100, v8
	s_ashr_i32 s15, s14, 31
	s_waitcnt vmcnt(0)
	ds_write2_b32 v9, v2, v3 offset1:1
	ds_write2_b32 v9, v4, v5 offset0:2 offset1:3
	v_ashrrev_i32_e32 v9, 4, v10
	v_add_u32_e32 v2, s14, v9
	v_ashrrev_i32_e32 v3, 31, v2
	v_lshlrev_b64 v[2:3], 12, v[2:3]
	v_lshl_add_u64 v[2:3], v[6:7], 0, v[2:3]
	v_mov_b32_e32 v2, v80
	v_mov_b32_e32 v3, v81
	v_mov_b32_e32 v4, v82
	v_mov_b32_e32 v5, v83
	v_mul_lo_u32 v9, v9, s77
	v_add3_u32 v9, s78, v9, v0
	s_waitcnt vmcnt(0)
	ds_write2_b32 v9, v2, v3 offset1:1
	ds_write2_b32 v9, v4, v5 offset0:2 offset1:3
	v_add_u32_e32 v2, 0x200, v8
	v_ashrrev_i32_e32 v9, 4, v2
	v_add_u32_e32 v2, s14, v9
	v_ashrrev_i32_e32 v3, 31, v2
	v_lshlrev_b64 v[2:3], 12, v[2:3]
	v_lshl_add_u64 v[2:3], v[6:7], 0, v[2:3]
	v_mov_b32_e32 v2, v84
	v_mov_b32_e32 v3, v85
	v_mov_b32_e32 v4, v86
	v_mov_b32_e32 v5, v87
	v_mul_lo_u32 v9, v9, s77
	v_add3_u32 v9, s78, v9, v0
	s_waitcnt vmcnt(0)
	ds_write2_b32 v9, v2, v3 offset1:1
	ds_write2_b32 v9, v4, v5 offset0:2 offset1:3
	v_add_u32_e32 v2, 0x300, v8
	v_ashrrev_i32_e32 v9, 4, v2
	v_add_u32_e32 v2, s14, v9
	v_ashrrev_i32_e32 v3, 31, v2
	v_lshlrev_b64 v[2:3], 12, v[2:3]
	v_lshl_add_u64 v[2:3], v[6:7], 0, v[2:3]
	v_mov_b32_e32 v2, v88
	v_mov_b32_e32 v3, v89
	v_mov_b32_e32 v4, v90
	v_mov_b32_e32 v5, v91
	v_mul_lo_u32 v6, v9, s77
	v_add3_u32 v0, s78, v6, v0
	s_lshl_b64 s[14:15], s[14:15], 1
	s_add_u32 s14, s26, s14
	s_addc_u32 s15, s27, s15
	s_waitcnt vmcnt(0)
	ds_write2_b32 v0, v2, v3 offset1:1
	ds_write2_b32 v0, v4, v5 offset0:2 offset1:3
	v_lshlrev_b32_e32 v0, 3, v8
	v_and_b32_e32 v0, 56, v0
	v_mul_u32_u24_e32 v4, 0x41, v0
	v_lshlrev_b32_e32 v0, 1, v0
	v_lshl_add_u64 v[2:3], s[14:15], 0, v[0:1]
	v_ashrrev_i32_e32 v0, 3, v8
	v_lshlrev_b32_e32 v5, 2, v0
	v_lshlrev_b32_e32 v11, 2, v4
	v_add3_u32 v8, s78, v5, v11
	s_waitcnt lgkmcnt(0)
	s_barrier
	ds_read2_b32 v[4:5], v8 offset1:65
	ds_read2_b32 v[6:7], v8 offset0:130 offset1:195
	v_add_u32_e32 v8, 0x400, v8
	s_waitcnt lgkmcnt(1)
	v_cvt_pk_bf16_f32 v4, v4, v5
	s_waitcnt lgkmcnt(0)
	v_cvt_pk_bf16_f32 v5, v6, v7
	ds_read2_b32 v[6:7], v8 offset0:4 offset1:69
	ds_read2_b32 v[8:9], v8 offset0:134 offset1:199
	s_waitcnt lgkmcnt(1)
	v_cvt_pk_bf16_f32 v6, v6, v7
	s_waitcnt lgkmcnt(0)
	v_cvt_pk_bf16_f32 v7, v8, v9
	v_add_u32_e32 v8, s12, v0
	v_ashrrev_i32_e32 v9, 31, v8
	v_lshlrev_b64 v[8:9], 11, v[8:9]
	v_lshl_add_u64 v[8:9], v[2:3], 0, v[8:9]
	v_ashrrev_i32_e32 v0, 3, v10
	global_store_dwordx4 v[8:9], v[4:7], off
	s_nop 1
	v_lshlrev_b32_e32 v4, 2, v0
	v_add3_u32 v8, s78, v4, v11
	ds_read2_b32 v[4:5], v8 offset1:65
	ds_read2_b32 v[6:7], v8 offset0:130 offset1:195
	v_add_u32_e32 v8, 0x400, v8
	s_waitcnt lgkmcnt(1)
	v_cvt_pk_bf16_f32 v4, v4, v5
	s_waitcnt lgkmcnt(0)
	v_cvt_pk_bf16_f32 v5, v6, v7
	ds_read2_b32 v[6:7], v8 offset0:4 offset1:69
	ds_read2_b32 v[8:9], v8 offset0:134 offset1:199
	s_waitcnt lgkmcnt(1)
	v_cvt_pk_bf16_f32 v6, v6, v7
	s_waitcnt lgkmcnt(0)
	v_cvt_pk_bf16_f32 v7, v8, v9
	v_add_u32_e32 v8, s12, v0
	v_ashrrev_i32_e32 v9, 31, v8
	v_lshlrev_b64 v[8:9], 11, v[8:9]
	v_lshl_add_u64 v[2:3], v[2:3], 0, v[8:9]
	global_store_dwordx4 v[2:3], v[4:7], off

.LBB0_462:
	s_andn2_b64 vcc, exec, s[12:13]
	s_cbranch_vccnz .LBB0_464
	s_load_dwordx2 s[12:13], s[58:59], 0x80
	s_lshr_b32 s80, s0, 9
	s_lshl_b64 s[14:15], s[80:81], 23
	v_mov_b32_e32 v8, v243
	s_waitcnt lgkmcnt(0)
	s_add_u32 s14, s12, s14
	s_addc_u32 s15, s13, s15
	s_lshl_b64 s[12:13], s[80:81], 22
	s_add_u32 s16, s28, s12
	s_addc_u32 s17, s29, s13
	s_and_b32 s0, s42, 0x7c0
	s_and_b32 s38, s48, 0x3c0
	s_lshl_b32 s12, s0, 2
	v_ashrrev_i32_e32 v9, 4, v8
	s_add_u32 s12, s14, s12
	v_lshlrev_b32_e32 v0, 4, v8
	v_add_u32_e32 v2, s38, v9
	s_addc_u32 s13, s15, 0
	v_and_b32_e32 v0, 0xf0, v0
	v_ashrrev_i32_e32 v3, 31, v2
	v_lshl_add_u64 v[6:7], s[12:13], 0, v[0:1]
	v_lshlrev_b64 v[2:3], 13, v[2:3]
	v_lshl_add_u64 v[2:3], v[6:7], 0, v[2:3]
	v_mov_b32_e32 v70, 0x20000
	v_mov_b32_e32 v71, 0
	v_lshl_add_u64 v[72:73], v[2:3], 0, v[70:71]
	v_lshl_add_u64 v[74:75], v[72:73], 0, v[70:71]
	v_lshl_add_u64 v[76:77], v[74:75], 0, v[70:71]
	s_barrier
	global_load_dwordx4 v[2:5], v[2:3], off
	global_load_dwordx4 v[80:83], v[72:73], off
	global_load_dwordx4 v[84:87], v[74:75], off
	global_load_dwordx4 v[88:91], v[76:77], off
	v_mul_lo_u32 v9, v9, s77
	v_add3_u32 v9, s78, v9, v0
	v_add_u32_e32 v10, 0x100, v8
	s_lshl_b32 s12, s38, 1
	s_add_u32 s12, s16, s12
	s_addc_u32 s13, s17, 0
	s_waitcnt vmcnt(0)
	ds_write2_b32 v9, v2, v3 offset1:1
	ds_write2_b32 v9, v4, v5 offset0:2 offset1:3
	v_ashrrev_i32_e32 v9, 4, v10
	v_add_u32_e32 v2, s38, v9
	v_ashrrev_i32_e32 v3, 31, v2
	v_lshlrev_b64 v[2:3], 13, v[2:3]
	v_lshl_add_u64 v[2:3], v[6:7], 0, v[2:3]
	v_mov_b32_e32 v2, v80
	v_mov_b32_e32 v3, v81
	v_mov_b32_e32 v4, v82
	v_mov_b32_e32 v5, v83
	v_mul_lo_u32 v9, v9, s77
	v_add3_u32 v9, s78, v9, v0
	s_waitcnt vmcnt(0)
	ds_write2_b32 v9, v2, v3 offset1:1
	ds_write2_b32 v9, v4, v5 offset0:2 offset1:3
	v_add_u32_e32 v2, 0x200, v8
	v_ashrrev_i32_e32 v9, 4, v2
	v_add_u32_e32 v2, s38, v9
	v_ashrrev_i32_e32 v3, 31, v2
	v_lshlrev_b64 v[2:3], 13, v[2:3]
	v_lshl_add_u64 v[2:3], v[6:7], 0, v[2:3]
	v_mov_b32_e32 v2, v84
	v_mov_b32_e32 v3, v85
	v_mov_b32_e32 v4, v86
	v_mov_b32_e32 v5, v87
	v_mul_lo_u32 v9, v9, s77
	v_add3_u32 v9, s78, v9, v0
	s_waitcnt vmcnt(0)
	ds_write2_b32 v9, v2, v3 offset1:1
	ds_write2_b32 v9, v4, v5 offset0:2 offset1:3
	v_add_u32_e32 v2, 0x300, v8
	v_ashrrev_i32_e32 v9, 4, v2
	v_add_u32_e32 v2, s38, v9
	v_ashrrev_i32_e32 v3, 31, v2
	v_lshlrev_b64 v[2:3], 13, v[2:3]
	v_lshl_add_u64 v[2:3], v[6:7], 0, v[2:3]
	v_mov_b32_e32 v2, v88
	v_mov_b32_e32 v3, v89
	v_mov_b32_e32 v4, v90
	v_mov_b32_e32 v5, v91
	v_mul_lo_u32 v6, v9, s77
	v_add3_u32 v0, s78, v6, v0
	s_waitcnt vmcnt(0)
	ds_write2_b32 v0, v2, v3 offset1:1
	ds_write2_b32 v0, v4, v5 offset0:2 offset1:3
	v_lshlrev_b32_e32 v0, 3, v8
	v_and_b32_e32 v0, 56, v0
	v_mul_u32_u24_e32 v4, 0x41, v0
	v_lshlrev_b32_e32 v0, 1, v0
	v_lshl_add_u64 v[2:3], s[12:13], 0, v[0:1]
	v_ashrrev_i32_e32 v0, 3, v8
	v_lshlrev_b32_e32 v5, 2, v0
	v_lshlrev_b32_e32 v11, 2, v4
	v_add3_u32 v8, s78, v5, v11
	s_waitcnt lgkmcnt(0)
	s_barrier
	ds_read2_b32 v[4:5], v8 offset1:65
	ds_read2_b32 v[6:7], v8 offset0:130 offset1:195
	v_add_u32_e32 v8, 0x400, v8
	s_waitcnt lgkmcnt(1)
	v_cvt_pk_bf16_f32 v4, v4, v5
	s_waitcnt lgkmcnt(0)
	v_cvt_pk_bf16_f32 v5, v6, v7
	ds_read2_b32 v[6:7], v8 offset0:4 offset1:69
	ds_read2_b32 v[8:9], v8 offset0:134 offset1:199
	s_waitcnt lgkmcnt(1)
	v_cvt_pk_bf16_f32 v6, v6, v7
	s_waitcnt lgkmcnt(0)
	v_cvt_pk_bf16_f32 v7, v8, v9
	v_add_u32_e32 v8, s0, v0
	v_ashrrev_i32_e32 v9, 31, v8
	v_lshlrev_b64 v[8:9], 11, v[8:9]
	v_lshl_add_u64 v[8:9], v[2:3], 0, v[8:9]
	v_ashrrev_i32_e32 v0, 3, v10
	global_store_dwordx4 v[8:9], v[4:7], off
	s_nop 1
	v_lshlrev_b32_e32 v4, 2, v0
	v_add3_u32 v8, s78, v4, v11
	ds_read2_b32 v[4:5], v8 offset1:65
	ds_read2_b32 v[6:7], v8 offset0:130 offset1:195
	v_add_u32_e32 v8, 0x400, v8
	s_waitcnt lgkmcnt(1)
	v_cvt_pk_bf16_f32 v4, v4, v5
	s_waitcnt lgkmcnt(0)
	v_cvt_pk_bf16_f32 v5, v6, v7
	ds_read2_b32 v[6:7], v8 offset0:4 offset1:69
	ds_read2_b32 v[8:9], v8 offset0:134 offset1:199
	s_waitcnt lgkmcnt(1)
	v_cvt_pk_bf16_f32 v6, v6, v7
	s_waitcnt lgkmcnt(0)
	v_cvt_pk_bf16_f32 v7, v8, v9
	v_add_u32_e32 v8, s0, v0
	v_ashrrev_i32_e32 v9, 31, v8
	v_lshlrev_b64 v[8:9], 11, v[8:9]
	v_lshl_add_u64 v[2:3], v[2:3], 0, v[8:9]
	global_store_dwordx4 v[2:3], v[4:7], off

.LBB0_465:
	s_andn2_b64 vcc, exec, s[12:13]
	s_cbranch_vccnz .LBB0_475
	s_load_dwordx2 s[12:13], s[58:59], 0x78
	s_load_dwordx2 s[38:39], s[58:59], 0x18
	v_mov_b32_e32 v10, v243
	s_waitcnt lgkmcnt(0)
	s_add_u32 s14, s12, s6
	s_addc_u32 s15, s13, s7
	s_lshl_b64 s[12:13], s[4:5], 2
	s_add_u32 s12, s38, s12
	s_addc_u32 s13, s39, s13
	s_and_b32 s0, s42, 0x3c0
	s_and_b32 s16, s45, 0x3c0
	s_lshl_b32 s17, s0, 2
	v_lshlrev_b32_e32 v0, 2, v10
	v_ashrrev_i32_e32 v11, 4, v10
	s_add_u32 s14, s14, s17
	v_and_b32_e32 v0, 60, v0
	v_add_u32_e32 v8, s16, v11
	s_addc_u32 s15, s15, 0
	v_lshlrev_b32_e32 v0, 2, v0
	v_ashrrev_i32_e32 v9, 31, v8
	v_lshl_add_u64 v[6:7], s[14:15], 0, v[0:1]
	v_lshlrev_b64 v[2:3], 12, v[8:9]
	v_lshl_add_u64 v[2:3], v[6:7], 0, v[2:3]
	v_mov_b32_e32 v70, 0x10000
	v_mov_b32_e32 v71, 0
	v_lshl_add_u64 v[72:73], v[2:3], 0, v[70:71]
	v_lshl_add_u64 v[74:75], v[72:73], 0, v[70:71]
	v_lshl_add_u64 v[76:77], v[74:75], 0, v[70:71]
	s_barrier
	global_load_dwordx4 v[2:5], v[2:3], off
	global_load_dwordx4 v[80:83], v[72:73], off
	global_load_dwordx4 v[84:87], v[74:75], off
	global_load_dwordx4 v[88:91], v[76:77], off
	s_cmp_lg_u64 s[38:39], 0
	s_cselect_b64 s[14:15], -1, 0
	s_cmp_eq_u64 s[38:39], 0
	s_cbranch_scc1 .LBB0_468
	v_lshl_add_u64 v[8:9], v[8:9], 2, s[12:13]
	global_load_dword v8, v[8:9], off
	s_waitcnt vmcnt(0)
	v_pk_mul_f32 v[4:5], v[4:5], v[8:9] op_sel_hi:[1,0]
	v_pk_mul_f32 v[2:3], v[2:3], v[8:9] op_sel_hi:[1,0]
.LBB0_468:
	v_mul_lo_u32 v8, v11, s77
	v_add_u32_e32 v11, 0x100, v10
	v_add3_u32 v8, s78, v8, v0
	v_ashrrev_i32_e32 v12, 4, v11
	s_waitcnt vmcnt(0)
	ds_write2_b32 v8, v2, v3 offset1:1
	ds_write2_b32 v8, v4, v5 offset0:2 offset1:3
	v_add_u32_e32 v8, s16, v12
	v_ashrrev_i32_e32 v9, 31, v8
	v_lshlrev_b64 v[2:3], 12, v[8:9]
	v_lshl_add_u64 v[2:3], v[6:7], 0, v[2:3]
	v_mov_b32_e32 v2, v80
	v_mov_b32_e32 v3, v81
	v_mov_b32_e32 v4, v82
	v_mov_b32_e32 v5, v83
	v_cndmask_b32_e64 v13, 0, 1, s[14:15]
	v_cmp_ne_u32_e64 s[38:39], 1, v13
	s_andn2_b64 vcc, exec, s[14:15]
	s_cbranch_vccnz .LBB0_470
	v_lshl_add_u64 v[8:9], v[8:9], 2, s[12:13]
	global_load_dword v8, v[8:9], off
	s_waitcnt vmcnt(0)
	v_pk_mul_f32 v[4:5], v[4:5], v[8:9] op_sel_hi:[1,0]
	v_pk_mul_f32 v[2:3], v[2:3], v[8:9] op_sel_hi:[1,0]
.LBB0_470:
	v_mul_lo_u32 v8, v12, s77
	v_add3_u32 v8, s78, v8, v0
	s_waitcnt vmcnt(0)
	ds_write2_b32 v8, v2, v3 offset1:1
	ds_write2_b32 v8, v4, v5 offset0:2 offset1:3
	v_add_u32_e32 v2, 0x200, v10
	v_ashrrev_i32_e32 v12, 4, v2
	v_add_u32_e32 v8, s16, v12
	v_ashrrev_i32_e32 v9, 31, v8
	v_lshlrev_b64 v[2:3], 12, v[8:9]
	v_lshl_add_u64 v[2:3], v[6:7], 0, v[2:3]
	v_mov_b32_e32 v2, v84
	v_mov_b32_e32 v3, v85
	v_mov_b32_e32 v4, v86
	v_mov_b32_e32 v5, v87
	s_and_b64 vcc, exec, s[38:39]
	s_cbranch_vccnz .LBB0_472
	v_lshl_add_u64 v[8:9], v[8:9], 2, s[12:13]
	global_load_dword v8, v[8:9], off
	s_waitcnt vmcnt(0)
	v_pk_mul_f32 v[4:5], v[4:5], v[8:9] op_sel_hi:[1,0]
	v_pk_mul_f32 v[2:3], v[2:3], v[8:9] op_sel_hi:[1,0]
.LBB0_472:
	v_mul_lo_u32 v8, v12, s77
	v_add3_u32 v8, s78, v8, v0
	s_waitcnt vmcnt(0)
	ds_write2_b32 v8, v2, v3 offset1:1
	ds_write2_b32 v8, v4, v5 offset0:2 offset1:3
	v_add_u32_e32 v2, 0x300, v10
	v_ashrrev_i32_e32 v12, 4, v2
	v_add_u32_e32 v8, s16, v12
	v_ashrrev_i32_e32 v9, 31, v8
	v_lshlrev_b64 v[2:3], 12, v[8:9]
	v_lshl_add_u64 v[2:3], v[6:7], 0, v[2:3]
	v_mov_b32_e32 v2, v88
	v_mov_b32_e32 v3, v89
	v_mov_b32_e32 v4, v90
	v_mov_b32_e32 v5, v91
	s_and_b64 vcc, exec, s[38:39]
	s_cbranch_vccnz .LBB0_474
	v_lshl_add_u64 v[6:7], v[8:9], 2, s[12:13]
	global_load_dword v6, v[6:7], off
	s_waitcnt vmcnt(0)
	v_pk_mul_f32 v[4:5], v[4:5], v[6:7] op_sel_hi:[1,0]
	v_pk_mul_f32 v[2:3], v[2:3], v[6:7] op_sel_hi:[1,0]

.LBB0_476:
	s_andn2_b64 vcc, exec, s[12:13]
	s_cbranch_vccnz .LBB0_478
	s_add_u32 s12, s58, s40
	s_addc_u32 s13, s59, 0
	s_load_dwordx2 s[12:13], s[12:13], 0x0
	v_mov_b32_e32 v8, v243
	s_waitcnt lgkmcnt(0)
	v_ashrrev_i32_e32 v9, 4, v8
	s_add_u32 s12, s12, s8
	s_addc_u32 s13, s13, s9
	s_and_b32 s0, s42, 0x3c0
	s_and_b32 s14, s45, 0x3c0
	s_lshl_b32 s15, s0, 2
	s_add_u32 s12, s12, s15
	v_lshlrev_b32_e32 v0, 4, v8
	v_add_u32_e32 v2, s14, v9
	s_addc_u32 s13, s13, 0
	v_and_b32_e32 v0, 0xf0, v0
	v_ashrrev_i32_e32 v3, 31, v2
	v_lshl_add_u64 v[6:7], s[12:13], 0, v[0:1]
	v_lshlrev_b64 v[2:3], 12, v[2:3]
	v_lshl_add_u64 v[2:3], v[6:7], 0, v[2:3]
	v_mov_b32_e32 v70, 0x10000
	v_mov_b32_e32 v71, 0
	v_lshl_add_u64 v[72:73], v[2:3], 0, v[70:71]
	v_lshl_add_u64 v[74:75], v[72:73], 0, v[70:71]
	v_lshl_add_u64 v[76:77], v[74:75], 0, v[70:71]
	s_barrier
	global_load_dwordx4 v[2:5], v[2:3], off
	global_load_dwordx4 v[80:83], v[72:73], off
	global_load_dwordx4 v[84:87], v[74:75], off
	global_load_dwordx4 v[88:91], v[76:77], off
	v_mul_lo_u32 v9, v9, s77
	v_add3_u32 v9, s78, v9, v0
	v_add_u32_e32 v10, 0x100, v8
	s_lshl_b32 s12, s14, 1
	s_add_u32 s12, s34, s12
	s_addc_u32 s13, s35, 0
	s_waitcnt vmcnt(0)
	ds_write2_b32 v9, v2, v3 offset1:1
	ds_write2_b32 v9, v4, v5 offset0:2 offset1:3
	v_ashrrev_i32_e32 v9, 4, v10
	v_add_u32_e32 v2, s14, v9
	v_ashrrev_i32_e32 v3, 31, v2
	v_lshlrev_b64 v[2:3], 12, v[2:3]
	v_lshl_add_u64 v[2:3], v[6:7], 0, v[2:3]
	v_mov_b32_e32 v2, v80
	v_mov_b32_e32 v3, v81
	v_mov_b32_e32 v4, v82
	v_mov_b32_e32 v5, v83
	v_mul_lo_u32 v9, v9, s77
	v_add3_u32 v9, s78, v9, v0
	s_waitcnt vmcnt(0)
	ds_write2_b32 v9, v2, v3 offset1:1
	ds_write2_b32 v9, v4, v5 offset0:2 offset1:3
	v_add_u32_e32 v2, 0x200, v8
	v_ashrrev_i32_e32 v9, 4, v2
	v_add_u32_e32 v2, s14, v9
	v_ashrrev_i32_e32 v3, 31, v2
	v_lshlrev_b64 v[2:3], 12, v[2:3]
	v_lshl_add_u64 v[2:3], v[6:7], 0, v[2:3]
	v_mov_b32_e32 v2, v84
	v_mov_b32_e32 v3, v85
	v_mov_b32_e32 v4, v86
	v_mov_b32_e32 v5, v87
	v_mul_lo_u32 v9, v9, s77
	v_add3_u32 v9, s78, v9, v0
	s_waitcnt vmcnt(0)
	ds_write2_b32 v9, v2, v3 offset1:1
	ds_write2_b32 v9, v4, v5 offset0:2 offset1:3
	v_add_u32_e32 v2, 0x300, v8
	v_ashrrev_i32_e32 v9, 4, v2
	v_add_u32_e32 v2, s14, v9
	v_ashrrev_i32_e32 v3, 31, v2
	v_lshlrev_b64 v[2:3], 12, v[2:3]
	v_lshl_add_u64 v[2:3], v[6:7], 0, v[2:3]
	v_mov_b32_e32 v2, v88
	v_mov_b32_e32 v3, v89
	v_mov_b32_e32 v4, v90
	v_mov_b32_e32 v5, v91
	v_mul_lo_u32 v6, v9, s77
	v_add3_u32 v0, s78, v6, v0
	s_waitcnt vmcnt(0)
	ds_write2_b32 v0, v2, v3 offset1:1
	ds_write2_b32 v0, v4, v5 offset0:2 offset1:3
	v_lshlrev_b32_e32 v0, 3, v8
	v_and_b32_e32 v0, 56, v0
	v_mul_u32_u24_e32 v4, 0x41, v0
	v_lshlrev_b32_e32 v0, 1, v0
	v_lshl_add_u64 v[2:3], s[12:13], 0, v[0:1]
	v_ashrrev_i32_e32 v0, 3, v8
	v_lshlrev_b32_e32 v5, 2, v0
	v_lshlrev_b32_e32 v11, 2, v4
	v_add3_u32 v8, s78, v5, v11
	s_waitcnt lgkmcnt(0)
	s_barrier
	ds_read2_b32 v[4:5], v8 offset1:65
	ds_read2_b32 v[6:7], v8 offset0:130 offset1:195
	v_add_u32_e32 v8, 0x400, v8
	s_waitcnt lgkmcnt(1)
	v_cvt_pk_bf16_f32 v4, v4, v5
	s_waitcnt lgkmcnt(0)
	v_cvt_pk_bf16_f32 v5, v6, v7
	ds_read2_b32 v[6:7], v8 offset0:4 offset1:69
	ds_read2_b32 v[8:9], v8 offset0:134 offset1:199
	s_waitcnt lgkmcnt(1)
	v_cvt_pk_bf16_f32 v6, v6, v7
	s_waitcnt lgkmcnt(0)
	v_cvt_pk_bf16_f32 v7, v8, v9
	v_add_u32_e32 v8, s0, v0
	v_ashrrev_i32_e32 v9, 31, v8
	v_lshlrev_b64 v[8:9], 11, v[8:9]
	v_lshl_add_u64 v[8:9], v[2:3], 0, v[8:9]
	v_ashrrev_i32_e32 v0, 3, v10
	global_store_dwordx4 v[8:9], v[4:7], off
	s_nop 1
	v_lshlrev_b32_e32 v4, 2, v0
	v_add3_u32 v8, s78, v4, v11
	ds_read2_b32 v[4:5], v8 offset1:65
	ds_read2_b32 v[6:7], v8 offset0:130 offset1:195
	v_add_u32_e32 v8, 0x400, v8
	s_waitcnt lgkmcnt(1)
	v_cvt_pk_bf16_f32 v4, v4, v5
	s_waitcnt lgkmcnt(0)
	v_cvt_pk_bf16_f32 v5, v6, v7
	ds_read2_b32 v[6:7], v8 offset0:4 offset1:69
	ds_read2_b32 v[8:9], v8 offset0:134 offset1:199
	s_waitcnt lgkmcnt(1)
	v_cvt_pk_bf16_f32 v6, v6, v7
	s_waitcnt lgkmcnt(0)
	v_cvt_pk_bf16_f32 v7, v8, v9
	v_add_u32_e32 v8, s0, v0
	v_ashrrev_i32_e32 v9, 31, v8
	v_lshlrev_b64 v[8:9], 11, v[8:9]
	v_lshl_add_u64 v[2:3], v[2:3], 0, v[8:9]
	global_store_dwordx4 v[2:3], v[4:7], off

.LBB0_479:
	s_andn2_b64 vcc, exec, s[12:13]
	s_cbranch_vccnz .LBB0_440
	s_add_u32 s12, s58, s41
	s_addc_u32 s13, s59, 0
	s_load_dwordx2 s[12:13], s[12:13], 0x0
	s_mul_hi_i32 s0, s11, 0x2aaaaaab
	s_load_dwordx2 s[38:39], s[58:59], 0x10
	v_mov_b32_e32 v10, v243
	s_waitcnt lgkmcnt(0)
	s_add_u32 s52, s12, s37
	s_addc_u32 s53, s13, s36
	s_lshl_b64 s[12:13], s[4:5], 2
	s_add_u32 s14, s38, s12
	s_addc_u32 s15, s39, s13
	s_lshr_b32 s12, s0, 31
	s_ashr_i32 s0, s0, 3
	s_add_i32 s0, s0, s12
	s_mul_i32 s13, s0, 0xfffff400
	s_add_i32 s16, s42, s13
	s_ashr_i32 s17, s16, 31
	s_lshl_b32 s12, s0, 6
	s_lshl_b64 s[16:17], s[16:17], 2
	v_lshlrev_b32_e32 v0, 2, v10
	s_add_u32 s16, s52, s16
	v_and_b32_e32 v0, 60, v0
	s_addc_u32 s17, s53, s17
	v_lshlrev_b32_e32 v0, 2, v0
	v_ashrrev_i32_e32 v11, 4, v10
	v_lshl_add_u64 v[6:7], s[16:17], 0, v[0:1]
	v_add_u32_e32 v8, s12, v11
	v_mad_i64_i32 v[2:3], s[16:17], v8, s76, v[6:7]
	v_mov_b32_e32 v70, s76
	v_lshlrev_b32_e32 v70, 4, v70
	v_mov_b32_e32 v71, 0
	v_lshl_add_u64 v[72:73], v[2:3], 0, v[70:71]
	v_lshl_add_u64 v[74:75], v[72:73], 0, v[70:71]
	v_lshl_add_u64 v[76:77], v[74:75], 0, v[70:71]
	s_barrier
	global_load_dwordx4 v[2:5], v[2:3], off
	global_load_dwordx4 v[80:83], v[72:73], off
	global_load_dwordx4 v[84:87], v[74:75], off
	global_load_dwordx4 v[88:91], v[76:77], off
	s_cmp_lg_u64 s[38:39], 0
	s_cselect_b64 s[16:17], -1, 0
	s_cmp_eq_u64 s[38:39], 0
	s_cbranch_scc1 .LBB0_482
	v_ashrrev_i32_e32 v9, 31, v8
	v_lshl_add_u64 v[8:9], v[8:9], 2, s[14:15]
	global_load_dword v8, v[8:9], off
	s_waitcnt vmcnt(0)
	v_pk_mul_f32 v[4:5], v[4:5], v[8:9] op_sel_hi:[1,0]
	v_pk_mul_f32 v[2:3], v[2:3], v[8:9] op_sel_hi:[1,0]
.LBB0_482:
	v_mul_lo_u32 v8, v11, s77
	v_add_u32_e32 v11, 0x100, v10
	v_add3_u32 v8, s78, v8, v0
	v_ashrrev_i32_e32 v12, 4, v11
	s_waitcnt vmcnt(0)
	ds_write2_b32 v8, v2, v3 offset1:1
	ds_write2_b32 v8, v4, v5 offset0:2 offset1:3
	v_add_u32_e32 v8, s12, v12
	v_mad_i64_i32 v[2:3], s[38:39], v8, s76, v[6:7]
	v_mov_b32_e32 v2, v80
	v_mov_b32_e32 v3, v81
	v_mov_b32_e32 v4, v82
	v_mov_b32_e32 v5, v83
	v_cndmask_b32_e64 v9, 0, 1, s[16:17]
	v_cmp_ne_u32_e64 s[38:39], 1, v9
	s_andn2_b64 vcc, exec, s[16:17]
	s_cbranch_vccnz .LBB0_484
	v_ashrrev_i32_e32 v9, 31, v8
	v_lshl_add_u64 v[8:9], v[8:9], 2, s[14:15]
	global_load_dword v8, v[8:9], off
	s_waitcnt vmcnt(0)
	v_pk_mul_f32 v[4:5], v[4:5], v[8:9] op_sel_hi:[1,0]
	v_pk_mul_f32 v[2:3], v[2:3], v[8:9] op_sel_hi:[1,0]
.LBB0_484:
	v_mul_lo_u32 v8, v12, s77
	v_add3_u32 v8, s78, v8, v0
	s_waitcnt vmcnt(0)
	ds_write2_b32 v8, v2, v3 offset1:1
	ds_write2_b32 v8, v4, v5 offset0:2 offset1:3
	v_add_u32_e32 v2, 0x200, v10
	v_ashrrev_i32_e32 v12, 4, v2
	v_add_u32_e32 v8, s12, v12
	v_mad_i64_i32 v[2:3], s[16:17], v8, s76, v[6:7]
	v_mov_b32_e32 v2, v84
	v_mov_b32_e32 v3, v85
	v_mov_b32_e32 v4, v86
	v_mov_b32_e32 v5, v87
	s_and_b64 vcc, exec, s[38:39]
	s_cbranch_vccnz .LBB0_486
	v_ashrrev_i32_e32 v9, 31, v8
	v_lshl_add_u64 v[8:9], v[8:9], 2, s[14:15]
	global_load_dword v8, v[8:9], off
	s_waitcnt vmcnt(0)
	v_pk_mul_f32 v[4:5], v[4:5], v[8:9] op_sel_hi:[1,0]
	v_pk_mul_f32 v[2:3], v[2:3], v[8:9] op_sel_hi:[1,0]
.LBB0_486:
	v_mul_lo_u32 v8, v12, s77
	v_add3_u32 v8, s78, v8, v0
	s_waitcnt vmcnt(0)
	ds_write2_b32 v8, v2, v3 offset1:1
	ds_write2_b32 v8, v4, v5 offset0:2 offset1:3
	v_add_u32_e32 v2, 0x300, v10
	v_ashrrev_i32_e32 v12, 4, v2
	v_add_u32_e32 v8, s12, v12
	v_mad_i64_i32 v[2:3], s[16:17], v8, s76, v[6:7]
	v_mov_b32_e32 v2, v88
	v_mov_b32_e32 v3, v89
	v_mov_b32_e32 v4, v90
	v_mov_b32_e32 v5, v91
	s_and_b64 vcc, exec, s[38:39]
	s_cbranch_vccnz .LBB0_439
	v_ashrrev_i32_e32 v9, 31, v8
	v_lshl_add_u64 v[6:7], v[8:9], 2, s[14:15]
	global_load_dword v6, v[6:7], off
	s_waitcnt vmcnt(0)
	v_pk_mul_f32 v[4:5], v[4:5], v[6:7] op_sel_hi:[1,0]
	v_pk_mul_f32 v[2:3], v[2:3], v[6:7] op_sel_hi:[1,0]
	s_branch .LBB0_439
